# v26 + hgC output tile loop unrolled wave-uniform (all LDS fragments in flight), hgC norm-gain loads hoisted and issued once, prep_item second token block constant loads batched into one round trip
# baseline (speedup 1.0000x reference)
; __device__ __forceinline__ void unpack8(const u32x4& w, f32x4& v0, f32x4& v1) { v0[0] = bflo(w.x); v0[1] = bfhi(w.x); v0[2] = bflo(w.y); v0[3] = bfhi(w.y); v1[0] = bflo(w.z); v1[1] = bfhi(w.z); v1[2] = bflo(w.w); v1[3] = bfhi(w.w); }
; __device__ __forceinline__ void prep_item(const Bufs& B, int l, int s, int it, unsigned char* shm, const bf16x8 (&w2f)[4][2], const bf16x8 (&a2f)[4][2], const PrepRegs& R) {
;     ...
;         for (int q = 0; q < 3; ++q) {
;             f32x4 c0v, c1v, p0v, p1v; unpack8(c3w[tt][q], c0v, c1v); unpack8(p3w[tt][q], p0v, p1v);
;             const f32x4 m0v = *(const f32x4*)(mu + q * 512 + c0), m1v = *(const f32x4*)(mu + q * 512 + c0 + 4);
;             const f32x4 x0 = c0v + m0v * (p0v - c0v), x1 = c1v + m1v * (p1v - c1v);
;             if (q == 0) { r[0] = x0; r[1] = x1; } else if (q == 1) { k[0] = x0; k[1] = x1; } else { v[0] = x0; v[1] = x1; }
;         }
;         f32x4 kk[2], kp[2], ka[2], wv[2], av[2];
;         float n2 = 0.f, c2 = 0.f, c3 = 0.f;
; #pragma unroll
;         for (int e = 0; e < 2; ++e) {
;             av[e] = *(const f32x4*)(Aa + t * 512 + c0 + 4 * e); wv[e] = *(const f32x4*)(Dd + t * 512 + c0 + 4 * e);
;             const f32x4 kkw = *(const f32x4*)(kkp + c0 + 4 * e), kaw = *(const f32x4*)(kap + c0 + 4 * e), rkw = *(const f32x4*)(rkp + c0 + 4 * e);
;             kk[e] = k[e] * kkw;
;             kp[e] = k[e] * (1.0f + (av[e] - 1.0f) * kaw);
; #pragma unroll
;             for (int j = 0; j < 4; ++j) { n2 += kk[e][j] * kk[e][j]; c2 += kp[e][j] * r[e][j]; c3 += r[e][j] * kp[e][j] * rkw[j]; }
;         }
.LBB0_522:
	s_or_b64 exec, exec, s[2:3]
	global_load_dwordx4 v[146:149], v[122:123], off offset:16
	global_load_dwordx4 v[150:153], v[122:123], off
	global_load_dwordx4 v[154:157], v[122:123], off offset:2064
	global_load_dwordx4 v[162:165], v[122:123], off offset:2048
	global_load_dwordx4 v[166:169], v[120:121], off
	global_load_dwordx4 v[170:173], v[120:121], off offset:16
	global_load_dwordx4 v[188:191], v[100:101], off offset:16
	global_load_dwordx4 v[192:195], v[100:101], off
	global_load_dwordx4 v[196:199], v[118:119], off offset:16
	global_load_dwordx4 v[218:221], v[118:119], off
	global_load_dwordx4 v[222:225], v[116:117], off offset:16
	global_load_dwordx4 v[226:229], v[116:117], off
	v_lshlrev_b32_e32 v96, 16, v92
	v_and_b32_e32 v97, 0xffff0000, v92
	v_lshlrev_b32_e32 v98, 16, v93
	v_and_b32_e32 v99, 0xffff0000, v93
	v_lshlrev_b32_e32 v104, 16, v94
	v_and_b32_e32 v105, 0xffff0000, v94
	v_lshlrev_b32_e32 v106, 16, v95
	v_and_b32_e32 v107, 0xffff0000, v95
	v_lshlrev_b32_e32 v103, 16, v88
	v_and_b32_e32 v108, 0xffff0000, v88
	v_lshlrev_b32_e32 v112, 16, v89
	v_and_b32_e32 v109, 0xffff0000, v89
	v_lshlrev_b32_e32 v113, 16, v90
	v_and_b32_e32 v114, 0xffff0000, v90
	v_lshlrev_b32_e32 v115, 16, v91
	v_and_b32_e32 v124, 0xffff0000, v91
	v_sub_f32_e32 v111, v108, v97
	v_sub_f32_e32 v110, v103, v96
	v_sub_f32_e32 v109, v109, v99
	v_sub_f32_e32 v108, v112, v98
	v_lshlrev_b32_e32 v103, 16, v82
	v_lshl_add_u32 v133, v133, 11, v102
	s_mov_b32 s2, 0xf800000
	v_ashrrev_i32_e32 v139, 31, v138
	s_waitcnt vmcnt(10)
	v_mov_b64_e32 v[88:89], v[146:147]
	v_mov_b64_e32 v[90:91], v[148:149]
	v_mov_b64_e32 v[92:93], v[150:151]
	v_mov_b64_e32 v[94:95], v[152:153]
	v_pk_fma_f32 v[108:109], v[108:109], v[94:95], v[98:99]
	v_pk_fma_f32 v[110:111], v[110:111], v[92:93], v[96:97]
	v_sub_f32_e32 v93, v114, v105
	v_sub_f32_e32 v92, v113, v104
	v_sub_f32_e32 v95, v124, v107
	v_sub_f32_e32 v94, v115, v106
	v_pk_fma_f32 v[112:113], v[94:95], v[90:91], v[106:107]
	v_pk_fma_f32 v[114:115], v[92:93], v[88:89], v[104:105]
	v_lshlrev_b32_e32 v88, 16, v84
	v_and_b32_e32 v89, 0xffff0000, v84
	v_lshlrev_b32_e32 v90, 16, v85
	v_and_b32_e32 v91, 0xffff0000, v85
	v_lshlrev_b32_e32 v92, 16, v86
	v_and_b32_e32 v93, 0xffff0000, v86
	v_lshlrev_b32_e32 v94, 16, v87
	v_and_b32_e32 v95, 0xffff0000, v87
	v_lshlrev_b32_e32 v98, 16, v80
	v_and_b32_e32 v99, 0xffff0000, v80
	v_lshlrev_b32_e32 v96, 16, v81
	v_and_b32_e32 v97, 0xffff0000, v81
	v_and_b32_e32 v104, 0xffff0000, v82
	v_lshlrev_b32_e32 v105, 16, v83
	v_and_b32_e32 v106, 0xffff0000, v83
	v_sub_f32_e32 v97, v97, v91
	v_sub_f32_e32 v96, v96, v90
	v_sub_f32_e32 v99, v99, v89
	v_sub_f32_e32 v98, v98, v88
	s_waitcnt vmcnt(8)
	v_mov_b64_e32 v[80:81], v[154:155]
	v_mov_b64_e32 v[82:83], v[156:157]
	v_mov_b64_e32 v[84:85], v[162:163]
	v_mov_b64_e32 v[86:87], v[164:165]
	v_pk_fma_f32 v[140:141], v[98:99], v[84:85], v[88:89]
	v_pk_fma_f32 v[142:143], v[96:97], v[86:87], v[90:91]
	v_sub_f32_e32 v85, v104, v93
	v_sub_f32_e32 v84, v103, v92
	v_sub_f32_e32 v87, v106, v95
	v_sub_f32_e32 v86, v105, v94
	v_pk_fma_f32 v[128:129], v[86:87], v[82:83], v[94:95]
	v_pk_fma_f32 v[130:131], v[84:85], v[80:81], v[92:93]
	v_lshlrev_b32_e32 v88, 16, v78
	v_and_b32_e32 v89, 0xffff0000, v78
	v_lshlrev_b32_e32 v90, 16, v79
	v_and_b32_e32 v91, 0xffff0000, v79
	v_lshlrev_b32_e32 v78, 16, v74
	v_and_b32_e32 v79, 0xffff0000, v74
	v_lshlrev_b32_e32 v74, 16, v75
	v_and_b32_e32 v75, 0xffff0000, v75
	v_sub_f32_e32 v89, v89, v79
	v_sub_f32_e32 v88, v88, v78
	v_sub_f32_e32 v91, v91, v75
	v_sub_f32_e32 v90, v90, v74
	s_waitcnt vmcnt(6)
	v_mov_b64_e32 v[80:81], v[166:167]
	v_mov_b64_e32 v[82:83], v[168:169]
	v_mov_b64_e32 v[84:85], v[170:171]
	v_mov_b64_e32 v[86:87], v[172:173]
	v_pk_fma_f32 v[120:121], v[90:91], v[86:87], v[74:75]
	v_pk_fma_f32 v[122:123], v[88:89], v[84:85], v[78:79]
	v_lshlrev_b32_e32 v78, 16, v76
	v_and_b32_e32 v76, 0xffff0000, v76
	v_lshlrev_b32_e32 v84, 16, v77
	v_and_b32_e32 v79, 0xffff0000, v77
	v_lshlrev_b32_e32 v74, 16, v72
	v_and_b32_e32 v75, 0xffff0000, v72
	v_lshlrev_b32_e32 v72, 16, v73
	v_and_b32_e32 v73, 0xffff0000, v73
	v_sub_f32_e32 v77, v76, v75
	v_sub_f32_e32 v76, v78, v74
	v_sub_f32_e32 v79, v79, v73
	v_sub_f32_e32 v78, v84, v72
	v_pk_fma_f32 v[124:125], v[78:79], v[82:83], v[72:73]
	v_pk_fma_f32 v[126:127], v[76:77], v[80:81], v[74:75]
	ds_read_b128 v[80:83], v133 offset:9216
	ds_read_b128 v[76:79], v133 offset:9232
	ds_read_b128 v[72:75], v133 offset:41984
	s_waitcnt lgkmcnt(2)
	v_pk_add_f32 v[118:119], v[80:81], -1.0 op_sel_hi:[1,0]
	v_pk_add_f32 v[116:117], v[82:83], -1.0 op_sel_hi:[1,0]
	s_waitcnt vmcnt(4)
	v_mov_b64_e32 v[84:85], v[188:189]
	v_mov_b64_e32 v[86:87], v[190:191]
	v_mov_b64_e32 v[100:101], v[192:193]
	v_mov_b64_e32 v[102:103], v[194:195]
	v_pk_mul_f32 v[100:101], v[140:141], v[100:101]
	v_pk_mul_f32 v[102:103], v[142:143], v[102:103]
	s_waitcnt vmcnt(2)
	v_mov_b64_e32 v[92:93], v[196:197]
	v_mov_b64_e32 v[94:95], v[198:199]
	v_mov_b64_e32 v[104:105], v[218:219]
	v_mov_b64_e32 v[106:107], v[220:221]
	v_pk_fma_f32 v[104:105], v[118:119], v[104:105], 1.0 op_sel_hi:[1,1,0]
	v_pk_fma_f32 v[106:107], v[116:117], v[106:107], 1.0 op_sel_hi:[1,1,0]
	v_pk_mul_f32 v[104:105], v[140:141], v[104:105]
	v_pk_mul_f32 v[106:107], v[142:143], v[106:107]
	v_mul_f32_e32 v116, v110, v104
	s_waitcnt vmcnt(0)
	v_mov_b64_e32 v[88:89], v[222:223]
	v_mov_b64_e32 v[90:91], v[224:225]
	v_mov_b64_e32 v[96:97], v[226:227]
	v_mov_b64_e32 v[98:99], v[228:229]
	v_fma_f32 v141, v96, v116, 0
	v_mul_f32_e32 v96, v111, v105
	v_mul_f32_e32 v116, v101, v101
	v_fmac_f32_e32 v141, v97, v96
	v_mul_f32_e32 v96, v108, v106
	v_fmac_f32_e32 v116, v100, v100
	v_fmac_f32_e32 v141, v98, v96
	v_pk_mul_f32 v[96:97], v[102:103], v[102:103]
	v_pk_mul_f32 v[118:119], v[128:129], v[86:87]
	s_waitcnt lgkmcnt(1)
; __device__ __forceinline__ u32x4 pack8(const f32x4& v0, const f32x4& v1) { u32x4 w; w.x = cvt_pk_bf16(v0[0], v0[1]); w.y = cvt_pk_bf16(v0[2], v0[3]); w.z = cvt_pk_bf16(v1[0], v1[1]); w.w = cvt_pk_bf16(v1[2], v1[3]); return w; }
; __device__ __forceinline__ float rsum8(float v) { v += dppf<0xB1>(v); v += dppf<0x4E>(v); v += dppf<0x141>(v); return v; }
; __device__ __forceinline__ void prep_item(const Bufs& B, int l, int s, int it, unsigned char* shm, const bf16x8 (&w2f)[4][2], const bf16x8 (&a2f)[4][2], const PrepRegs& R) {
;     ...
;         f32x4 kk[2], kp[2], ka[2], wv[2], av[2];
;         float n2 = 0.f, c2 = 0.f, c3 = 0.f;
; #pragma unroll
;         for (int e = 0; e < 2; ++e) {
;             av[e] = *(const f32x4*)(Aa + t * 512 + c0 + 4 * e); wv[e] = *(const f32x4*)(Dd + t * 512 + c0 + 4 * e);
;             const f32x4 kkw = *(const f32x4*)(kkp + c0 + 4 * e), kaw = *(const f32x4*)(kap + c0 + 4 * e), rkw = *(const f32x4*)(rkp + c0 + 4 * e);
;             kk[e] = k[e] * kkw;
;             kp[e] = k[e] * (1.0f + (av[e] - 1.0f) * kaw);
; #pragma unroll
;             for (int j = 0; j < 4; ++j) { n2 += kk[e][j] * kk[e][j]; c2 += kp[e][j] * r[e][j]; c3 += r[e][j] * kp[e][j] * rkw[j]; }
;         }
;         n2 = rsum8(n2); c2 = rsum8(c2); c3 = rsum8(c3);
;         const float inv = 1.0f / fmaxf(sqrtf(n2), 1e-12f);
;         float c1 = 0.f;
; #pragma unroll
;         for (int e = 0; e < 2; ++e) { kk[e] = kk[e] * inv; ka[e] = kk[e] * av[e];
; #pragma unroll
;             for (int j = 0; j < 4; ++j) c1 += ka[e][j] * r[e][j]; }
;         c1 = rsum8(c1);
;         const size_t o = (size_t)m * 512 + c0;
;         *(f32x4*)(B.Wf + o) = wv[0]; *(f32x4*)(B.Wf + o + 4) = wv[1];
;         *(u32x4*)(B.KK + o) = pack8(kk[0], kk[1]);
;         *(u32x4*)(B.KK + VEC_STRIDE + o) = pack8(wv[0] * r[0], wv[1] * r[1]);
;         *(u32x4*)(B.KK + 2 * VEC_STRIDE + o) = pack8(ka[0], ka[1]);
;         *(u32x4*)(B.KK + 3 * VEC_STRIDE + o) = pack8(kp[0], kp[1]);
;         *(u32x4*)(B.V + o) = pack8(v[0], v[1]);
;         if ((lane & 7) == 0) { B.C1[m * 8 + h] = c1; B.C2[m * 8 + h] = c2; B.C3[m * 8 + h] = c3; }
	v_pk_add_f32 v[86:87], v[76:77], -1.0 op_sel_hi:[1,0]
	v_add_f32_e32 v96, v96, v116
	v_pk_mul_f32 v[116:117], v[130:131], v[84:85]
	v_pk_add_f32 v[84:85], v[78:79], -1.0 op_sel_hi:[1,0]
	v_pk_fma_f32 v[86:87], v[86:87], v[92:93], 1.0 op_sel_hi:[1,1,0]
	v_add_f32_e32 v142, v97, v96
	v_mul_f32_e32 v96, v109, v107
	v_pk_fma_f32 v[84:85], v[84:85], v[94:95], 1.0 op_sel_hi:[1,1,0]
	v_pk_mul_f32 v[94:95], v[130:131], v[86:87]
	v_pk_mul_f32 v[86:87], v[116:117], v[116:117]
	v_fmac_f32_e32 v141, v99, v96
	v_pk_mul_f32 v[92:93], v[128:129], v[84:85]
	v_mul_f32_e32 v84, v114, v94
	v_add_f32_e32 v86, v142, v86
	v_fmac_f32_e32 v141, v88, v84
	v_pk_mul_f32 v[84:85], v[118:119], v[118:119]
	v_add_f32_e32 v86, v87, v86
	v_add_f32_e32 v84, v84, v86
	v_add_f32_e32 v84, v85, v84
	v_mul_f32_e32 v87, v115, v95
	v_fmac_f32_e32 v141, v89, v87
	v_add_f32_dpp v84, v84, v84 quad_perm:[1,0,3,2] row_mask:0xf bank_mask:0xf bound_ctrl:1
	v_mul_f32_e32 v87, v112, v92
	v_fmac_f32_e32 v141, v90, v87
	v_add_f32_dpp v84, v84, v84 quad_perm:[2,3,0,1] row_mask:0xf bank_mask:0xf bound_ctrl:1
	v_mul_f32_e32 v85, v113, v93
	v_fmac_f32_e32 v141, v91, v85
	v_add_f32_dpp v88, v84, v84 row_half_mirror row_mask:0xf bank_mask:0xf bound_ctrl:1
	v_cmp_gt_f32_e32 vcc, s2, v88
	v_mul_f32_e32 v89, 0x4f800000, v88
	v_fma_f32 v140, v110, v104, 0
	v_cndmask_b32_e32 v88, v88, v89, vcc
	v_sqrt_f32_e32 v89, v88
	v_fmac_f32_e32 v140, v111, v105
	ds_read_b128 v[96:99], v133 offset:42000
	v_fmac_f32_e32 v140, v108, v106
	v_add_u32_e32 v90, -1, v89
	v_fma_f32 v91, -v90, v89, v88
	v_cmp_ge_f32_e64 s[40:41], 0, v91
	v_add_u32_e32 v91, 1, v89
	v_fmac_f32_e32 v140, v109, v107
	v_cndmask_b32_e64 v90, v89, v90, s[40:41]
	v_fma_f32 v89, -v91, v89, v88
	v_cmp_lt_f32_e64 s[40:41], 0, v89
	v_fmac_f32_e32 v140, v114, v94
	v_fmac_f32_e32 v140, v115, v95
	v_cndmask_b32_e64 v89, v90, v91, s[40:41]
	v_mul_f32_e32 v90, 0x37800000, v89
	v_cndmask_b32_e32 v89, v89, v90, vcc
	v_cmp_class_f32_e32 vcc, v88, v203
	v_fmac_f32_e32 v140, v112, v92
	v_fmac_f32_e32 v140, v113, v93
	v_cndmask_b32_e32 v88, v89, v88, vcc
	v_max_f32_e32 v88, 0x2b8cbccc, v88
	v_div_scale_f32 v89, s[2:3], v88, v88, 1.0
	v_rcp_f32_e32 v90, v89
	v_add_f32_dpp v84, v140, v140 quad_perm:[1,0,3,2] row_mask:0xf bank_mask:0xf bound_ctrl:1
	v_add_f32_dpp v86, v141, v141 quad_perm:[1,0,3,2] row_mask:0xf bank_mask:0xf bound_ctrl:1
	v_fma_f32 v91, -v89, v90, 1.0
	v_fmac_f32_e32 v90, v91, v90
	v_div_scale_f32 v91, vcc, 1.0, v88, 1.0
	v_mul_f32_e32 v128, v91, v90
	v_fma_f32 v129, -v89, v128, v91
	v_fmac_f32_e32 v128, v129, v90
	v_fma_f32 v89, -v89, v128, v91
	v_div_fmas_f32 v89, v89, v90, v128
	v_div_fixup_f32 v88, v89, v88, 1.0
	v_pk_mul_f32 v[90:91], v[100:101], v[88:89] op_sel_hi:[1,0]
	v_pk_mul_f32 v[100:101], v[102:103], v[88:89] op_sel_hi:[1,0]
	v_pk_mul_f32 v[102:103], v[80:81], v[90:91]
	v_pk_mul_f32 v[82:83], v[82:83], v[100:101]
	v_fma_f32 v128, v110, v102, 0
	v_fmac_f32_e32 v128, v111, v103
	v_fmac_f32_e32 v128, v108, v82
	v_pk_mul_f32 v[80:81], v[116:117], v[88:89] op_sel_hi:[1,0]
	v_fmac_f32_e32 v128, v109, v83
	v_pk_mul_f32 v[88:89], v[118:119], v[88:89] op_sel_hi:[1,0]
	v_pk_mul_f32 v[118:119], v[76:77], v[80:81]
	v_pk_mul_f32 v[116:117], v[78:79], v[88:89]
	v_fmac_f32_e32 v128, v114, v118
	v_fmac_f32_e32 v128, v115, v119
	v_fmac_f32_e32 v128, v112, v116
	v_fmac_f32_e32 v128, v113, v117
	v_cvt_pk_bf16_f32 v80, v80, v81
	v_cvt_pk_bf16_f32 v81, v88, v89
	v_add_f32_dpp v76, v128, v128 quad_perm:[1,0,3,2] row_mask:0xf bank_mask:0xf bound_ctrl:1
	v_lshlrev_b64 v[128:129], 9, v[138:139]
	v_or_b32_e32 v128, v128, v144
	v_lshl_add_u64 v[78:79], v[128:129], 2, s[60:61]
	v_lshlrev_b64 v[88:89], 1, v[128:129]
	s_waitcnt lgkmcnt(1)
	global_store_dwordx4 v[78:79], v[72:75], off
	s_waitcnt lgkmcnt(0)
	global_store_dwordx4 v[78:79], v[96:99], off offset:16
	v_cvt_pk_bf16_f32 v78, v90, v91
	v_cvt_pk_bf16_f32 v79, v100, v101
	v_lshl_add_u64 v[90:91], s[52:53], 0, v[88:89]
	global_store_dwordx4 v[90:91], v[78:81], off
	v_pk_mul_f32 v[74:75], v[108:109], v[74:75]
	v_pk_mul_f32 v[72:73], v[110:111], v[72:73]
	v_pk_mul_f32 v[78:79], v[112:113], v[98:99]
	v_pk_mul_f32 v[80:81], v[114:115], v[96:97]
	v_cvt_pk_bf16_f32 v72, v72, v73
	v_cvt_pk_bf16_f32 v73, v74, v75
	v_cvt_pk_bf16_f32 v74, v80, v81
	v_cvt_pk_bf16_f32 v75, v78, v79
	v_lshl_add_u64 v[78:79], s[70:71], 0, v[88:89]
	global_store_dwordx4 v[78:79], v[72:75], off
	v_lshl_add_u64 v[78:79], s[36:37], 0, v[88:89]
	v_add_f32_dpp v84, v84, v84 quad_perm:[2,3,0,1] row_mask:0xf bank_mask:0xf bound_ctrl:1
	v_cvt_pk_bf16_f32 v72, v102, v103
	v_cvt_pk_bf16_f32 v73, v82, v83
	v_cvt_pk_bf16_f32 v74, v118, v119
	v_cvt_pk_bf16_f32 v75, v116, v117
	v_add_f32_dpp v86, v86, v86 quad_perm:[2,3,0,1] row_mask:0xf bank_mask:0xf bound_ctrl:1
	v_add_f32_dpp v76, v76, v76 quad_perm:[2,3,0,1] row_mask:0xf bank_mask:0xf bound_ctrl:1
	global_store_dwordx4 v[78:79], v[72:75], off
	v_lshl_add_u64 v[78:79], s[20:21], 0, v[88:89]
	v_mov_b32_dpp v85, v84 row_half_mirror row_mask:0xf bank_mask:0xf bound_ctrl:1
	v_cvt_pk_bf16_f32 v72, v104, v105
	v_cvt_pk_bf16_f32 v73, v106, v107
	v_cvt_pk_bf16_f32 v74, v94, v95
	v_cvt_pk_bf16_f32 v75, v92, v93
	v_mov_b32_dpp v87, v86 row_half_mirror row_mask:0xf bank_mask:0xf bound_ctrl:1
	v_mov_b32_dpp v77, v76 row_half_mirror row_mask:0xf bank_mask:0xf bound_ctrl:1
	global_store_dwordx4 v[78:79], v[72:75], off
	v_lshl_add_u64 v[78:79], s[62:63], 0, v[88:89]
	s_nop 0
	v_cvt_pk_bf16_f32 v72, v126, v127
	v_cvt_pk_bf16_f32 v73, v124, v125
	v_cvt_pk_bf16_f32 v74, v122, v123
	v_cvt_pk_bf16_f32 v75, v120, v121
	global_store_dwordx4 v[78:79], v[72:75], off
	s_and_saveexec_b64 s[2:3], s[38:39]
	s_cbranch_execz .LBB0_524
	v_lshl_or_b32 v72, v138, 3, v137
	v_ashrrev_i32_e32 v73, 31, v72
	v_lshlrev_b64 v[72:73], 2, v[72:73]
	v_add_f32_e32 v76, v76, v77
	v_lshl_add_u64 v[74:75], s[56:57], 0, v[72:73]
	v_add_f32_e32 v78, v86, v87
	v_add_f32_e32 v79, v84, v85
	global_store_dword v[74:75], v76, off
	v_lshl_add_u64 v[74:75], s[50:51], 0, v[72:73]
	v_lshl_add_u64 v[72:73], s[58:59], 0, v[72:73]
	global_store_dword v[74:75], v79, off
	global_store_dword v[72:73], v78, off

; __device__ __forceinline__ u32x4 pack8(const f32x4& v0, const f32x4& v1) { u32x4 w; w.x = cvt_pk_bf16(v0[0], v0[1]); w.y = cvt_pk_bf16(v0[2], v0[3]); w.z = cvt_pk_bf16(v1[0], v1[1]); w.w = cvt_pk_bf16(v1[2], v1[3]); return w; }
; __device__ __forceinline__ void hgC_item(const Bufs& B, int l, int it, unsigned char* shm, const float* hlb, const float* hn) {
;     ...
; #pragma unroll
;     for (int q = 0; q < 2; ++q) {
;         const int idx = tid + 512 * q, t = idx >> 4, v8 = (idx & 15) * 8;
;         f32x4 o0 = *(const f32x4*)(oS + t * 132 + v8), o1 = *(const f32x4*)(oS + t * 132 + v8 + 4);
;         float ssq = o0[0] * o0[0] + o0[1] * o0[1] + o0[2] * o0[2] + o0[3] * o0[3] + o1[0] * o1[0] + o1[1] * o1[1] + o1[2] * o1[2] + o1[3] * o1[3];
;         ssq = rsum16(ssq);
;         const float rs = rsqrtf(ssq * (1.0f / 128.0f) + 1e-6f);
;         const f32x4 n0 = *(const f32x4*)(hn + h * 128 + v8), n1 = *(const f32x4*)(hn + h * 128 + v8 + 4);
;         *(u32x4*)(B.br + 3 * VEC_STRIDE + (size_t)(m0 + t) * 512 + h * 128 + v8) = pack8(o0 * rs * n0, o1 * rs * n1);
;     }
.LBB0_819:
	s_waitcnt lgkmcnt(0)
	s_barrier
	v_mad_u64_u32 v[12:13], s[34:35], v43, s85, v[48:49]
	v_mad_u64_u32 v[20:21], s[34:35], v49, s85, v[48:49]
	ds_read_b128 v[8:11], v12
	ds_read_b128 v[12:15], v12 offset:16
	ds_read_b128 v[16:19], v20
	ds_read_b128 v[20:23], v20 offset:16
	v_lshlrev_b64 v[24:25], 10, v[46:47]
	s_brev_b32 s34, 60
	s_waitcnt lgkmcnt(3)
	v_mov_b32_e32 v37, v9
	s_waitcnt lgkmcnt(1)
	v_mov_b32_e32 v36, v17
	v_pk_mul_f32 v[26:27], v[10:11], v[10:11]
	v_pk_mul_f32 v[32:33], v[18:19], v[18:19]
	v_mov_b32_e32 v34, v16
	v_mov_b32_e32 v35, v8
	v_pk_mul_f32 v[36:37], v[36:37], v[36:37]
	v_mov_b32_e32 v46, v32
	v_mov_b32_e32 v47, v26
	v_pk_fma_f32 v[34:35], v[34:35], v[34:35], v[36:37]
	v_pk_mul_f32 v[30:31], v[12:13], v[12:13]
	s_waitcnt lgkmcnt(0)
	v_pk_mul_f32 v[40:41], v[20:21], v[20:21]
	v_mov_b32_e32 v26, v33
	v_pk_add_f32 v[34:35], v[46:47], v[34:35]
	v_mov_b32_e32 v32, v40
	v_mov_b32_e32 v33, v30
	v_pk_add_f32 v[26:27], v[26:27], v[34:35]
	v_pk_mul_f32 v[28:29], v[14:15], v[14:15]
	v_pk_mul_f32 v[38:39], v[22:23], v[22:23]
	v_mov_b32_e32 v30, v41
	v_pk_add_f32 v[26:27], v[32:33], v[26:27]
	v_mov_b32_e32 v40, v38
	v_mov_b32_e32 v41, v28
	v_pk_add_f32 v[26:27], v[30:31], v[26:27]
	v_mov_b32_e32 v28, v39
	v_pk_add_f32 v[26:27], v[40:41], v[26:27]
	v_lshl_add_u64 v[24:25], s[22:23], 0, v[24:25]
	v_pk_add_f32 v[26:27], v[28:29], v[26:27]
	v_mov_b32_e32 v43, v177
	v_lshl_add_u64 v[24:25], v[24:25], 0, s[30:31]
	v_mov_b32_dpp v29, v27 quad_perm:[1,0,3,2] row_mask:0xf bank_mask:0xf bound_ctrl:1
	v_mov_b32_dpp v28, v26 quad_perm:[1,0,3,2] row_mask:0xf bank_mask:0xf bound_ctrl:1
	v_pk_add_f32 v[26:27], v[26:27], v[28:29]
	v_lshl_add_u64 v[24:25], v[24:25], 0, v[42:43]
	s_add_i32 s18, s18, s72
	v_mov_b32_dpp v29, v27 quad_perm:[2,3,0,1] row_mask:0xf bank_mask:0xf bound_ctrl:1
	v_mov_b32_dpp v28, v26 quad_perm:[2,3,0,1] row_mask:0xf bank_mask:0xf bound_ctrl:1
	v_pk_add_f32 v[26:27], v[26:27], v[28:29]
	s_cmpk_lt_i32 s18, 0x400
	s_nop 0
	v_mov_b32_dpp v29, v27 row_half_mirror row_mask:0xf bank_mask:0xf bound_ctrl:1
	v_mov_b32_dpp v28, v26 row_half_mirror row_mask:0xf bank_mask:0xf bound_ctrl:1
	v_pk_add_f32 v[26:27], v[26:27], v[28:29]
	s_nop 1
	v_mov_b32_dpp v29, v27 row_mirror row_mask:0xf bank_mask:0xf bound_ctrl:1
	v_mov_b32_dpp v28, v26 row_mirror row_mask:0xf bank_mask:0xf bound_ctrl:1
	v_pk_add_f32 v[26:27], v[26:27], v[28:29]
	s_nop 0
	v_pk_fma_f32 v[26:27], v[26:27], s[34:35], v[178:179] op_sel_hi:[1,0,0]
	s_nop 0
	v_mul_f32_e32 v28, 0x4b800000, v27
	v_cmp_gt_f32_e32 vcc, s33, v27
	s_nop 1
	v_cndmask_b32_e32 v27, v27, v28, vcc
	v_rsq_f32_e32 v27, v27
	s_nop 0
	v_mul_f32_e32 v28, 0x45800000, v27
	v_cndmask_b32_e32 v28, v27, v28, vcc
	v_pk_mul_f32 v[8:9], v[8:9], v[28:29] op_sel_hi:[1,0]
	v_pk_mul_f32 v[10:11], v[10:11], v[28:29] op_sel_hi:[1,0]
	v_pk_mul_f32 v[12:13], v[12:13], v[28:29] op_sel_hi:[1,0]
	v_pk_mul_f32 v[14:15], v[14:15], v[28:29] op_sel_hi:[1,0]
	v_cmp_gt_f32_e32 vcc, s33, v26
	s_waitcnt vmcnt(0)
	v_pk_mul_f32 v[2:3], v[54:55], v[10:11]
	v_pk_mul_f32 v[0:1], v[52:53], v[8:9]
	v_pk_mul_f32 v[6:7], v[58:59], v[14:15]
	v_pk_mul_f32 v[4:5], v[56:57], v[12:13]
	v_cvt_pk_bf16_f32 v0, v0, v1
	v_cvt_pk_bf16_f32 v1, v2, v3
	v_cvt_pk_bf16_f32 v2, v4, v5
	v_cvt_pk_bf16_f32 v3, v6, v7
	global_store_dwordx4 v[24:25], v[0:3], off
	s_nop 0
	v_mul_f32_e32 v10, 0x4b800000, v26
	v_cndmask_b32_e32 v10, v26, v10, vcc
	v_rsq_f32_e32 v10, v10
	v_lshlrev_b64 v[8:9], 10, v[44:45]
	v_lshl_add_u64 v[8:9], s[22:23], 0, v[8:9]
	v_lshl_add_u64 v[8:9], v[8:9], 0, s[30:31]
	v_mul_f32_e32 v11, 0x45800000, v10
	v_cndmask_b32_e32 v10, v10, v11, vcc
	v_pk_mul_f32 v[12:13], v[16:17], v[10:11] op_sel_hi:[1,0]
	v_pk_mul_f32 v[14:15], v[18:19], v[10:11] op_sel_hi:[1,0]
	v_pk_mul_f32 v[16:17], v[20:21], v[10:11] op_sel_hi:[1,0]
	v_pk_mul_f32 v[10:11], v[22:23], v[10:11] op_sel_hi:[1,0]
	v_lshl_add_u64 v[8:9], v[8:9], 0, v[42:43]
	v_pk_mul_f32 v[2:3], v[54:55], v[14:15]
	v_pk_mul_f32 v[0:1], v[52:53], v[12:13]
	v_pk_mul_f32 v[6:7], v[58:59], v[10:11]
	v_pk_mul_f32 v[4:5], v[56:57], v[16:17]
	v_cvt_pk_bf16_f32 v0, v0, v1
	v_cvt_pk_bf16_f32 v1, v2, v3
	v_cvt_pk_bf16_f32 v2, v4, v5
	v_cvt_pk_bf16_f32 v3, v6, v7
	global_store_dwordx4 v[8:9], v[0:3], off
	s_cbranch_scc0 .LBB0_836

; __device__ __forceinline__ void hgC_item(const Bufs& B, int l, int it, unsigned char* shm, const float* hlb, const float* hn) {
;     ...
;     for (int tile = wid; tile < 32; tile += 8) {
;         const int tm = tile >> 3, tn = tile & 7;
;         const f32x4 acc = mma_tile_pre<4>(qe + tm * 16 * 136, 136, sf, lane) + mma_tile64<false, true>(P, tm * 16, iT, tn * 16, lane);
; #pragma unroll
;         for (int j = 0; j < 4; ++j) oS[(tm * 16 + (lane >> 4) * 4 + j) * 132 + tn * 16 + (lane & 15)] = acc[j];
;     }
;     ...
;         const f32x4 n0 = *(const f32x4*)(hn + h * 128 + v8), n1 = *(const f32x4*)(hn + h * 128 + v8 + 4);
.LBB0_833:
	s_or_b64 exec, exec, s[2:3]
	s_waitcnt lgkmcnt(0)
	s_barrier
	s_lshl_b32 s36, s19, 2
	s_add_u32 s36, s44, s36
	s_addc_u32 s37, s45, 0
	v_lshlrev_b32_e32 v50, 2, v65
	global_load_dwordx4 v[52:55], v50, s[36:37]
	global_load_dwordx4 v[56:59], v50, s[36:37] offset:16
	v_mad_u32_u24 v16, v21, s77, v176
	v_mad_u32_u24 v18, v21, s76, v176
	v_lshl_or_b32 v20, v66, 4, v21
	v_mov_b32_e32 v19, s84
	v_or_b32_e32 v17, 32, v64
	v_add_u32_e32 v18, s47, v18
	v_mad_u32_u24 v22, v20, s76, v19
	v_bitop3_b32 v24, v20, v64, 56 bitop3:0x6c
	v_bitop3_b32 v25, v20, v17, 56 bitop3:0x6c
	v_lshl_add_u32 v24, v24, 1, v22
	v_lshl_add_u32 v25, v25, 1, v22
	ds_read_b128 v[28:31], v24
	ds_read_b128 v[32:35], v25
	ds_read_b128 v[80:83], v16 offset:33792
	ds_read_b128 v[84:87], v16 offset:38144
	ds_read_b128 v[88:91], v16 offset:42496
	ds_read_b128 v[92:95], v16 offset:46848
	ds_read_b128 v[96:99], v16 offset:33856
	ds_read_b128 v[100:103], v16 offset:38208
	ds_read_b128 v[104:107], v16 offset:42560
	ds_read_b128 v[108:111], v16 offset:46912
	ds_read_b128 v[112:115], v16 offset:33920
	ds_read_b128 v[116:119], v16 offset:38272
	ds_read_b128 v[120:123], v16 offset:42624
	ds_read_b128 v[124:127], v16 offset:46976
	v_mov_b32_e32 v27, s85
	v_mul_u32_u24_e32 v26, v23, v27
	v_lshl_add_u32 v26, v66, 6, v26
	v_lshl_add_u32 v26, v21, 2, v26
	s_waitcnt lgkmcnt(8)
	v_mfma_f32_16x16x32_bf16 v[60:63], v[80:83], v[0:3], 0
	v_mfma_f32_16x16x32_bf16 v[68:71], v[84:87], v[0:3], 0
	v_mfma_f32_16x16x32_bf16 v[72:75], v[88:91], v[0:3], 0
	v_mfma_f32_16x16x32_bf16 v[76:79], v[92:95], v[0:3], 0
	ds_read_b128 v[80:83], v16 offset:33984
	ds_read_b128 v[84:87], v16 offset:38336
	ds_read_b128 v[88:91], v16 offset:42688
	ds_read_b128 v[92:95], v16 offset:47040
	s_waitcnt lgkmcnt(8)
	v_mfma_f32_16x16x32_bf16 v[60:63], v[96:99], v[4:7], v[60:63]
	v_mfma_f32_16x16x32_bf16 v[68:71], v[100:103], v[4:7], v[68:71]
	v_mfma_f32_16x16x32_bf16 v[72:75], v[104:107], v[4:7], v[72:75]
	v_mfma_f32_16x16x32_bf16 v[76:79], v[108:111], v[4:7], v[76:79]
	ds_read_b128 v[96:99], v18 offset:0
	ds_read_b128 v[100:103], v18 offset:2304
	ds_read_b128 v[104:107], v18 offset:4608
	ds_read_b128 v[108:111], v18 offset:6912
	s_waitcnt lgkmcnt(8)
	v_mfma_f32_16x16x32_bf16 v[60:63], v[112:115], v[8:11], v[60:63]
	v_mfma_f32_16x16x32_bf16 v[68:71], v[116:119], v[8:11], v[68:71]
	v_mfma_f32_16x16x32_bf16 v[72:75], v[120:123], v[8:11], v[72:75]
	v_mfma_f32_16x16x32_bf16 v[76:79], v[124:127], v[8:11], v[76:79]
	ds_read_b128 v[112:115], v18 offset:64
	ds_read_b128 v[116:119], v18 offset:2368
	ds_read_b128 v[120:123], v18 offset:4672
	ds_read_b128 v[124:127], v18 offset:6976
	s_waitcnt lgkmcnt(8)
	v_mfma_f32_16x16x32_bf16 v[60:63], v[80:83], v[12:15], v[60:63]
	v_mfma_f32_16x16x32_bf16 v[68:71], v[84:87], v[12:15], v[68:71]
	v_mfma_f32_16x16x32_bf16 v[72:75], v[88:91], v[12:15], v[72:75]
	v_mfma_f32_16x16x32_bf16 v[76:79], v[92:95], v[12:15], v[76:79]
	s_waitcnt lgkmcnt(4)
	v_mfma_f32_16x16x32_bf16 v[60:63], v[96:99], v[28:31], v[60:63]
	v_mfma_f32_16x16x32_bf16 v[68:71], v[100:103], v[28:31], v[68:71]
	v_mfma_f32_16x16x32_bf16 v[72:75], v[104:107], v[28:31], v[72:75]
	v_mfma_f32_16x16x32_bf16 v[76:79], v[108:111], v[28:31], v[76:79]
	s_waitcnt lgkmcnt(0)
	v_mfma_f32_16x16x32_bf16 v[60:63], v[112:115], v[32:35], v[60:63]
	v_mfma_f32_16x16x32_bf16 v[68:71], v[116:119], v[32:35], v[68:71]
	v_mfma_f32_16x16x32_bf16 v[72:75], v[120:123], v[32:35], v[72:75]
	v_mfma_f32_16x16x32_bf16 v[76:79], v[124:127], v[32:35], v[76:79]
	s_nop 7
	s_nop 3
	ds_write_b32 v26, v60
	ds_write_b32 v26, v61 offset:528
	ds_write_b32 v26, v62 offset:1056
	ds_write_b32 v26, v63 offset:1584
	ds_write_b32 v26, v68 offset:8448
	ds_write_b32 v26, v69 offset:8976
	ds_write_b32 v26, v70 offset:9504
	ds_write_b32 v26, v71 offset:10032
	ds_write_b32 v26, v72 offset:16896
	ds_write_b32 v26, v73 offset:17424
	ds_write_b32 v26, v74 offset:17952
	ds_write_b32 v26, v75 offset:18480
	ds_write_b32 v26, v76 offset:25344
	ds_write_b32 v26, v77 offset:25872
	ds_write_b32 v26, v78 offset:26400
	ds_write_b32 v26, v79 offset:26928
	s_branch .LBB0_819
